# GEMM loops: adjacent s_setprio 0/s_setprio 1 pairs between the two MFMA groups of a phase removed
# baseline (speedup 1.0000x reference)
.LBB0_146:
	ds_read_b128 v[128:131], v188
	ds_read_b128 v[132:135], v188 offset:1024
	ds_read_b128 v[136:139], v188 offset:2048
	ds_read_b128 v[140:143], v188 offset:3072
	ds_read_b128 v[144:147], v189
	ds_read_b128 v[148:151], v189 offset:1024
	ds_read_b128 v[176:179], v189 offset:2048
	ds_read_b128 v[180:183], v189 offset:3072
	s_add_u32 s50, s48, 0x100
	s_addc_u32 s51, s49, 0
	s_cmp_eq_u32 s57, 28
	s_cselect_b32 s55, s21, s51
	s_cselect_b32 s54, s20, s50
	s_cselect_b32 s53, s23, s56
	s_cselect_b32 s52, s22, s27
	v_lshl_add_u64 v[184:185], s[48:49], 0, v[170:171]
	s_add_i32 m0, s60, 0xc000
	ds_read_b128 v[194:197], v190
	ds_read_b128 v[198:201], v190 offset:1024
	ds_read_b128 v[202:205], v190 offset:2048
	ds_read_b128 v[206:209], v190 offset:3072
	ds_read_b128 v[210:213], v190 offset:4096
	ds_read_b128 v[214:217], v190 offset:5120
	ds_read_b128 v[218:221], v190 offset:6144
	ds_read_b128 v[222:225], v190 offset:7168
	global_load_lds_dwordx4 v[184:185], off
	v_lshl_add_u64 v[184:185], s[48:49], 0, v[172:173]
	s_add_i32 m0, s60, 0xe000
	s_nop 0
	global_load_lds_dwordx4 v[184:185], off
	s_waitcnt vmcnt(8)
	s_waitcnt lgkmcnt(0)
	s_barrier
	s_setprio 1
	s_waitcnt lgkmcnt(0)
	v_mfma_f32_16x16x32_bf16 v[120:123], v[128:131], v[194:197], v[120:123]
	v_mfma_f32_16x16x32_bf16 v[124:127], v[136:139], v[194:197], v[124:127]
	v_mfma_f32_16x16x32_bf16 v[108:111], v[128:131], v[202:205], v[108:111]
	v_mfma_f32_16x16x32_bf16 v[104:107], v[136:139], v[202:205], v[104:107]
	v_mfma_f32_16x16x32_bf16 v[92:95], v[128:131], v[210:213], v[92:95]
	v_mfma_f32_16x16x32_bf16 v[88:91], v[136:139], v[210:213], v[88:91]
	v_mfma_f32_16x16x32_bf16 v[76:79], v[128:131], v[218:221], v[76:79]
	v_mfma_f32_16x16x32_bf16 v[72:75], v[136:139], v[218:221], v[72:75]
	v_mfma_f32_16x16x32_bf16 v[120:123], v[132:135], v[198:201], v[120:123]
	v_mfma_f32_16x16x32_bf16 v[124:127], v[140:143], v[198:201], v[124:127]
	v_mfma_f32_16x16x32_bf16 v[108:111], v[132:135], v[206:209], v[108:111]
	v_mfma_f32_16x16x32_bf16 v[104:107], v[140:143], v[206:209], v[104:107]
	v_mfma_f32_16x16x32_bf16 v[92:95], v[132:135], v[214:217], v[92:95]
	v_mfma_f32_16x16x32_bf16 v[88:91], v[140:143], v[214:217], v[88:91]
	v_mfma_f32_16x16x32_bf16 v[76:79], v[132:135], v[222:225], v[76:79]
	v_mfma_f32_16x16x32_bf16 v[72:75], v[140:143], v[222:225], v[72:75]
	v_mfma_f32_16x16x32_bf16 v[112:115], v[144:147], v[194:197], v[112:115]
	v_mfma_f32_16x16x32_bf16 v[116:119], v[176:179], v[194:197], v[116:119]
	v_mfma_f32_16x16x32_bf16 v[100:103], v[144:147], v[202:205], v[100:103]
	v_mfma_f32_16x16x32_bf16 v[96:99], v[176:179], v[202:205], v[96:99]
	v_mfma_f32_16x16x32_bf16 v[84:87], v[144:147], v[210:213], v[84:87]
	v_mfma_f32_16x16x32_bf16 v[80:83], v[176:179], v[210:213], v[80:83]
	v_mfma_f32_16x16x32_bf16 v[68:71], v[144:147], v[218:221], v[68:71]
	v_mfma_f32_16x16x32_bf16 v[64:67], v[176:179], v[218:221], v[64:67]
	v_mfma_f32_16x16x32_bf16 v[112:115], v[148:151], v[198:201], v[112:115]
	v_mfma_f32_16x16x32_bf16 v[116:119], v[180:183], v[198:201], v[116:119]
	v_mfma_f32_16x16x32_bf16 v[100:103], v[148:151], v[206:209], v[100:103]
	v_mfma_f32_16x16x32_bf16 v[96:99], v[180:183], v[206:209], v[96:99]
	v_mfma_f32_16x16x32_bf16 v[84:87], v[148:151], v[214:217], v[84:87]
	v_mfma_f32_16x16x32_bf16 v[80:83], v[180:183], v[214:217], v[80:83]
	v_mfma_f32_16x16x32_bf16 v[68:71], v[148:151], v[222:225], v[68:71]
	v_mfma_f32_16x16x32_bf16 v[64:67], v[180:183], v[222:225], v[64:67]
	s_setprio 0
	s_barrier
	s_add_i32 s48, s71, s3
	v_lshl_add_u64 v[184:185], s[52:53], 0, v[154:155]
	s_mov_b32 m0, s48
	ds_read_b128 v[194:197], v190 offset:16384
	ds_read_b128 v[198:201], v190 offset:17408
	ds_read_b128 v[202:205], v190 offset:18432
	ds_read_b128 v[206:209], v190 offset:19456
	ds_read_b128 v[210:213], v190 offset:20480
	ds_read_b128 v[214:217], v190 offset:21504
	ds_read_b128 v[218:221], v190 offset:22528
	ds_read_b128 v[222:225], v190 offset:23552
	global_load_lds_dwordx4 v[184:185], off
	s_add_i32 m0, s48, 0x2000
	s_add_u32 s48, s52, 0x80000
	v_lshl_add_u64 v[226:227], s[52:53], 0, v[158:159]
	s_addc_u32 s49, s53, 0
	s_add_i32 s58, s72, s3
	global_load_lds_dwordx4 v[226:227], off
	v_lshl_add_u64 v[228:229], s[48:49], 0, v[154:155]
	s_mov_b32 m0, s58
	v_lshl_add_u64 v[230:231], s[54:55], 0, v[156:157]
	global_load_lds_dwordx4 v[228:229], off
	v_lshl_add_u64 v[228:229], s[48:49], 0, v[158:159]
	s_add_i32 m0, s58, 0x2000
	s_nop 0
	global_load_lds_dwordx4 v[228:229], off
	v_lshl_add_u64 v[228:229], s[54:55], 0, v[152:153]
	s_mov_b32 m0, s60
	s_nop 0
	global_load_lds_dwordx4 v[228:229], off
	s_mov_b32 m0, s61
	s_nop 0
	global_load_lds_dwordx4 v[230:231], off
	s_waitcnt vmcnt(8)
	s_waitcnt lgkmcnt(0)
	s_barrier
	s_setprio 1
	s_waitcnt lgkmcnt(0)
	v_mfma_f32_16x16x32_bf16 v[60:63], v[128:131], v[194:197], v[60:63]
	v_mfma_f32_16x16x32_bf16 v[56:59], v[136:139], v[194:197], v[56:59]
	v_mfma_f32_16x16x32_bf16 v[44:47], v[128:131], v[202:205], v[44:47]
	v_mfma_f32_16x16x32_bf16 v[40:43], v[136:139], v[202:205], v[40:43]
	v_mfma_f32_16x16x32_bf16 v[28:31], v[128:131], v[210:213], v[28:31]
	v_mfma_f32_16x16x32_bf16 v[24:27], v[136:139], v[210:213], v[24:27]
	v_mfma_f32_16x16x32_bf16 v[12:15], v[128:131], v[218:221], v[12:15]
	v_mfma_f32_16x16x32_bf16 v[8:11], v[136:139], v[218:221], v[8:11]
	v_mfma_f32_16x16x32_bf16 v[60:63], v[132:135], v[198:201], v[60:63]
	v_mfma_f32_16x16x32_bf16 v[56:59], v[140:143], v[198:201], v[56:59]
	v_mfma_f32_16x16x32_bf16 v[44:47], v[132:135], v[206:209], v[44:47]
	v_mfma_f32_16x16x32_bf16 v[40:43], v[140:143], v[206:209], v[40:43]
	v_mfma_f32_16x16x32_bf16 v[28:31], v[132:135], v[214:217], v[28:31]
	v_mfma_f32_16x16x32_bf16 v[24:27], v[140:143], v[214:217], v[24:27]
	v_mfma_f32_16x16x32_bf16 v[12:15], v[132:135], v[222:225], v[12:15]
	v_mfma_f32_16x16x32_bf16 v[8:11], v[140:143], v[222:225], v[8:11]
	v_mfma_f32_16x16x32_bf16 v[52:55], v[144:147], v[194:197], v[52:55]
	v_mfma_f32_16x16x32_bf16 v[48:51], v[176:179], v[194:197], v[48:51]
	v_mfma_f32_16x16x32_bf16 v[36:39], v[144:147], v[202:205], v[36:39]
	v_mfma_f32_16x16x32_bf16 v[32:35], v[176:179], v[202:205], v[32:35]
	v_mfma_f32_16x16x32_bf16 v[20:23], v[144:147], v[210:213], v[20:23]
	v_mfma_f32_16x16x32_bf16 v[16:19], v[176:179], v[210:213], v[16:19]
	v_mfma_f32_16x16x32_bf16 v[4:7], v[144:147], v[218:221], v[4:7]
	v_mfma_f32_16x16x32_bf16 v[0:3], v[176:179], v[218:221], v[0:3]
	v_mfma_f32_16x16x32_bf16 v[52:55], v[148:151], v[198:201], v[52:55]
	v_mfma_f32_16x16x32_bf16 v[48:51], v[180:183], v[198:201], v[48:51]
	v_mfma_f32_16x16x32_bf16 v[36:39], v[148:151], v[206:209], v[36:39]
	v_mfma_f32_16x16x32_bf16 v[32:35], v[180:183], v[206:209], v[32:35]
	v_mfma_f32_16x16x32_bf16 v[20:23], v[148:151], v[214:217], v[20:23]
	v_mfma_f32_16x16x32_bf16 v[16:19], v[180:183], v[214:217], v[16:19]
	v_mfma_f32_16x16x32_bf16 v[4:7], v[148:151], v[222:225], v[4:7]
	v_mfma_f32_16x16x32_bf16 v[0:3], v[180:183], v[222:225], v[0:3]
	s_setprio 0
	s_barrier
	s_add_i32 s58, 0, 0x18000
	s_add_i32 s59, 0, 0x1c000
	v_add_u32_e32 v140, s58, v186
	v_add_u32_e32 v160, s59, v186
	ds_read_b128 v[128:131], v140
	ds_read_b128 v[132:135], v140 offset:1024
	ds_read_b128 v[136:139], v140 offset:2048
	ds_read_b128 v[140:143], v140 offset:3072
	ds_read_b128 v[144:147], v160
	ds_read_b128 v[148:151], v160 offset:1024
	ds_read_b128 v[176:179], v160 offset:2048
	ds_read_b128 v[180:183], v160 offset:3072
	s_add_u32 s48, s54, 0xa0000
	s_addc_u32 s49, s55, 0
	s_mov_b32 m0, s62
	v_lshl_add_u64 v[232:233], s[48:49], 0, v[152:153]
	ds_read_b128 v[194:197], v190 offset:32768
	ds_read_b128 v[198:201], v190 offset:33792
	ds_read_b128 v[202:205], v190 offset:34816
	ds_read_b128 v[206:209], v190 offset:35840
	ds_read_b128 v[210:213], v190 offset:36864
	ds_read_b128 v[214:217], v190 offset:37888
	ds_read_b128 v[218:221], v190 offset:38912
	ds_read_b128 v[222:225], v190 offset:39936
	global_load_lds_dwordx4 v[232:233], off
	v_lshl_add_u64 v[232:233], s[48:49], 0, v[156:157]
	s_mov_b32 m0, s63
	s_nop 0
	global_load_lds_dwordx4 v[232:233], off
	s_waitcnt vmcnt(8)
	s_waitcnt lgkmcnt(0)
	s_barrier
	s_setprio 1
	s_waitcnt lgkmcnt(0)
	v_mfma_f32_16x16x32_bf16 v[120:123], v[128:131], v[194:197], v[120:123]
	v_mfma_f32_16x16x32_bf16 v[124:127], v[136:139], v[194:197], v[124:127]
	v_mfma_f32_16x16x32_bf16 v[108:111], v[128:131], v[202:205], v[108:111]
	v_mfma_f32_16x16x32_bf16 v[104:107], v[136:139], v[202:205], v[104:107]
	v_mfma_f32_16x16x32_bf16 v[92:95], v[128:131], v[210:213], v[92:95]
	v_mfma_f32_16x16x32_bf16 v[88:91], v[136:139], v[210:213], v[88:91]
	v_mfma_f32_16x16x32_bf16 v[76:79], v[128:131], v[218:221], v[76:79]
	v_mfma_f32_16x16x32_bf16 v[72:75], v[136:139], v[218:221], v[72:75]
	v_mfma_f32_16x16x32_bf16 v[120:123], v[132:135], v[198:201], v[120:123]
	v_mfma_f32_16x16x32_bf16 v[124:127], v[140:143], v[198:201], v[124:127]
	v_mfma_f32_16x16x32_bf16 v[108:111], v[132:135], v[206:209], v[108:111]
	v_mfma_f32_16x16x32_bf16 v[104:107], v[140:143], v[206:209], v[104:107]
	v_mfma_f32_16x16x32_bf16 v[92:95], v[132:135], v[214:217], v[92:95]
	v_mfma_f32_16x16x32_bf16 v[88:91], v[140:143], v[214:217], v[88:91]
	v_mfma_f32_16x16x32_bf16 v[76:79], v[132:135], v[222:225], v[76:79]
	v_mfma_f32_16x16x32_bf16 v[72:75], v[140:143], v[222:225], v[72:75]
	v_mfma_f32_16x16x32_bf16 v[112:115], v[144:147], v[194:197], v[112:115]
	v_mfma_f32_16x16x32_bf16 v[116:119], v[176:179], v[194:197], v[116:119]
	v_mfma_f32_16x16x32_bf16 v[100:103], v[144:147], v[202:205], v[100:103]
	v_mfma_f32_16x16x32_bf16 v[96:99], v[176:179], v[202:205], v[96:99]
	v_mfma_f32_16x16x32_bf16 v[84:87], v[144:147], v[210:213], v[84:87]
	v_mfma_f32_16x16x32_bf16 v[80:83], v[176:179], v[210:213], v[80:83]
	v_mfma_f32_16x16x32_bf16 v[68:71], v[144:147], v[218:221], v[68:71]
	v_mfma_f32_16x16x32_bf16 v[64:67], v[176:179], v[218:221], v[64:67]
	v_mfma_f32_16x16x32_bf16 v[112:115], v[148:151], v[198:201], v[112:115]
	v_mfma_f32_16x16x32_bf16 v[116:119], v[180:183], v[198:201], v[116:119]
	v_mfma_f32_16x16x32_bf16 v[100:103], v[148:151], v[206:209], v[100:103]
	v_mfma_f32_16x16x32_bf16 v[96:99], v[180:183], v[206:209], v[96:99]
	v_mfma_f32_16x16x32_bf16 v[84:87], v[148:151], v[214:217], v[84:87]
	v_mfma_f32_16x16x32_bf16 v[80:83], v[180:183], v[214:217], v[80:83]
	v_mfma_f32_16x16x32_bf16 v[68:71], v[148:151], v[222:225], v[68:71]
	v_mfma_f32_16x16x32_bf16 v[64:67], v[180:183], v[222:225], v[64:67]
	s_setprio 0
	s_barrier
	s_add_i32 s48, s58, s3
	v_lshl_add_u64 v[184:185], v[184:185], 0, s[14:15]
	s_mov_b32 m0, s48
	ds_read_b128 v[194:197], v190 offset:49152
	ds_read_b128 v[198:201], v190 offset:50176
	ds_read_b128 v[202:205], v190 offset:51200
	ds_read_b128 v[206:209], v190 offset:52224
	ds_read_b128 v[210:213], v190 offset:53248
	ds_read_b128 v[214:217], v190 offset:54272
	ds_read_b128 v[218:221], v190 offset:55296
	ds_read_b128 v[222:225], v190 offset:56320
	global_load_lds_dwordx4 v[184:185], off
	s_add_i32 m0, s48, 0x2000
	s_add_u32 s48, s52, 0x80080
	v_lshl_add_u64 v[184:185], v[226:227], 0, s[14:15]
	s_addc_u32 s49, s53, 0
	s_add_i32 s52, s59, s3
	global_load_lds_dwordx4 v[184:185], off
	v_lshl_add_u64 v[184:185], s[48:49], 0, v[154:155]
	s_mov_b32 m0, s52
	s_nop 0
	global_load_lds_dwordx4 v[184:185], off
	v_lshl_add_u64 v[184:185], s[48:49], 0, v[158:159]
	s_add_i32 m0, s52, 0x2000
	s_nop 0
	global_load_lds_dwordx4 v[184:185], off
	v_lshl_add_u64 v[184:185], v[228:229], 0, s[14:15]
	s_mov_b32 m0, s66
	s_nop 0
	global_load_lds_dwordx4 v[184:185], off
	v_lshl_add_u64 v[184:185], v[230:231], 0, s[14:15]
	s_mov_b32 m0, s67
	s_nop 0
	global_load_lds_dwordx4 v[184:185], off
	s_waitcnt vmcnt(8)
	s_waitcnt lgkmcnt(0)
	s_barrier
	s_setprio 1
	s_waitcnt lgkmcnt(0)
	v_mfma_f32_16x16x32_bf16 v[60:63], v[128:131], v[194:197], v[60:63]
	v_mfma_f32_16x16x32_bf16 v[56:59], v[136:139], v[194:197], v[56:59]
	v_mfma_f32_16x16x32_bf16 v[44:47], v[128:131], v[202:205], v[44:47]
	v_mfma_f32_16x16x32_bf16 v[40:43], v[136:139], v[202:205], v[40:43]
	v_mfma_f32_16x16x32_bf16 v[28:31], v[128:131], v[210:213], v[28:31]
	v_mfma_f32_16x16x32_bf16 v[24:27], v[136:139], v[210:213], v[24:27]
	v_mfma_f32_16x16x32_bf16 v[12:15], v[128:131], v[218:221], v[12:15]
	v_mfma_f32_16x16x32_bf16 v[8:11], v[136:139], v[218:221], v[8:11]
	v_mfma_f32_16x16x32_bf16 v[60:63], v[132:135], v[198:201], v[60:63]
	v_mfma_f32_16x16x32_bf16 v[56:59], v[140:143], v[198:201], v[56:59]
	v_mfma_f32_16x16x32_bf16 v[44:47], v[132:135], v[206:209], v[44:47]
	v_mfma_f32_16x16x32_bf16 v[40:43], v[140:143], v[206:209], v[40:43]
	v_mfma_f32_16x16x32_bf16 v[28:31], v[132:135], v[214:217], v[28:31]
	v_mfma_f32_16x16x32_bf16 v[24:27], v[140:143], v[214:217], v[24:27]
	v_mfma_f32_16x16x32_bf16 v[12:15], v[132:135], v[222:225], v[12:15]
	v_mfma_f32_16x16x32_bf16 v[8:11], v[140:143], v[222:225], v[8:11]
	v_mfma_f32_16x16x32_bf16 v[52:55], v[144:147], v[194:197], v[52:55]
	v_mfma_f32_16x16x32_bf16 v[48:51], v[176:179], v[194:197], v[48:51]
	v_mfma_f32_16x16x32_bf16 v[36:39], v[144:147], v[202:205], v[36:39]
	v_mfma_f32_16x16x32_bf16 v[32:35], v[176:179], v[202:205], v[32:35]
	v_mfma_f32_16x16x32_bf16 v[20:23], v[144:147], v[210:213], v[20:23]
	v_mfma_f32_16x16x32_bf16 v[16:19], v[176:179], v[210:213], v[16:19]
	v_mfma_f32_16x16x32_bf16 v[4:7], v[144:147], v[218:221], v[4:7]
	v_mfma_f32_16x16x32_bf16 v[0:3], v[176:179], v[218:221], v[0:3]
	v_mfma_f32_16x16x32_bf16 v[52:55], v[148:151], v[198:201], v[52:55]
	v_mfma_f32_16x16x32_bf16 v[48:51], v[180:183], v[198:201], v[48:51]
	v_mfma_f32_16x16x32_bf16 v[36:39], v[148:151], v[206:209], v[36:39]
	v_mfma_f32_16x16x32_bf16 v[32:35], v[180:183], v[206:209], v[32:35]
	v_mfma_f32_16x16x32_bf16 v[20:23], v[148:151], v[214:217], v[20:23]
	v_mfma_f32_16x16x32_bf16 v[16:19], v[180:183], v[214:217], v[16:19]
	v_mfma_f32_16x16x32_bf16 v[4:7], v[148:151], v[222:225], v[4:7]
	v_mfma_f32_16x16x32_bf16 v[0:3], v[180:183], v[222:225], v[0:3]
	s_setprio 0
	s_barrier
	s_add_i32 s57, s57, 2
	s_add_u32 s27, s27, 0x100
	s_addc_u32 s56, s56, 0
	s_cmp_gt_u32 s57, 29
	s_mov_b64 s[48:49], s[50:51]
	s_cbranch_scc0 .LBB0_146
	s_and_b64 vcc, exec, s[18:19]
	s_cbranch_vccz .LBB0_149
	s_barrier

.LBB0_250:
	ds_read_b128 v[148:151], v142
	ds_read_b128 v[152:155], v142 offset:1024
	ds_read_b128 v[156:159], v142 offset:2048
	ds_read_b128 v[160:163], v142 offset:3072
	ds_read_b128 v[164:167], v143
	ds_read_b128 v[168:171], v143 offset:1024
	ds_read_b128 v[176:179], v143 offset:2048
	ds_read_b128 v[180:183], v143 offset:3072
	s_add_i32 s20, s18, 0xf4f60080
	s_cmp_lg_u32 s52, 28
	s_cselect_b32 s20, s20, 0
	s_add_u32 s22, s2, s20
	s_addc_u32 s23, s3, 0
	s_add_u32 s20, s12, s20
	s_addc_u32 s21, s13, 0
	s_mov_b32 m0, s53
	v_lshl_add_u64 v[172:173], v[138:139], 0, s[18:19]
	ds_read_b128 v[188:191], v144
	ds_read_b128 v[192:195], v144 offset:1024
	ds_read_b128 v[196:199], v144 offset:2048
	ds_read_b128 v[200:203], v144 offset:3072
	ds_read_b128 v[204:207], v144 offset:4096
	ds_read_b128 v[208:211], v144 offset:5120
	ds_read_b128 v[212:215], v144 offset:6144
	ds_read_b128 v[216:219], v144 offset:7168
	global_load_lds_dwordx4 v[172:173], off
	v_lshl_add_u64 v[172:173], v[140:141], 0, s[18:19]
	s_mov_b32 m0, s54
	s_nop 0
	global_load_lds_dwordx4 v[172:173], off
	s_waitcnt vmcnt(8)
	s_waitcnt lgkmcnt(0)
	s_barrier
	s_setprio 1
	s_waitcnt lgkmcnt(0)
	v_mfma_f32_16x16x32_bf16 v[124:127], v[148:151], v[188:191], v[124:127]
	v_mfma_f32_16x16x32_bf16 v[120:123], v[156:159], v[188:191], v[120:123]
	v_mfma_f32_16x16x32_bf16 v[116:119], v[148:151], v[196:199], v[116:119]
	v_mfma_f32_16x16x32_bf16 v[112:115], v[156:159], v[196:199], v[112:115]
	v_mfma_f32_16x16x32_bf16 v[100:103], v[148:151], v[204:207], v[100:103]
	v_mfma_f32_16x16x32_bf16 v[96:99], v[156:159], v[204:207], v[96:99]
	v_mfma_f32_16x16x32_bf16 v[84:87], v[148:151], v[212:215], v[84:87]
	v_mfma_f32_16x16x32_bf16 v[80:83], v[156:159], v[212:215], v[80:83]
	v_mfma_f32_16x16x32_bf16 v[124:127], v[152:155], v[192:195], v[124:127]
	v_mfma_f32_16x16x32_bf16 v[120:123], v[160:163], v[192:195], v[120:123]
	v_mfma_f32_16x16x32_bf16 v[116:119], v[152:155], v[200:203], v[116:119]
	v_mfma_f32_16x16x32_bf16 v[112:115], v[160:163], v[200:203], v[112:115]
	v_mfma_f32_16x16x32_bf16 v[100:103], v[152:155], v[208:211], v[100:103]
	v_mfma_f32_16x16x32_bf16 v[96:99], v[160:163], v[208:211], v[96:99]
	v_mfma_f32_16x16x32_bf16 v[84:87], v[152:155], v[216:219], v[84:87]
	v_mfma_f32_16x16x32_bf16 v[80:83], v[160:163], v[216:219], v[80:83]
	v_mfma_f32_16x16x32_bf16 v[108:111], v[164:167], v[188:191], v[108:111]
	v_mfma_f32_16x16x32_bf16 v[104:107], v[176:179], v[188:191], v[104:107]
	v_mfma_f32_16x16x32_bf16 v[92:95], v[164:167], v[196:199], v[92:95]
	v_mfma_f32_16x16x32_bf16 v[88:91], v[176:179], v[196:199], v[88:91]
	v_mfma_f32_16x16x32_bf16 v[76:79], v[164:167], v[204:207], v[76:79]
	v_mfma_f32_16x16x32_bf16 v[72:75], v[176:179], v[204:207], v[72:75]
	v_mfma_f32_16x16x32_bf16 v[68:71], v[164:167], v[212:215], v[68:71]
	v_mfma_f32_16x16x32_bf16 v[64:67], v[176:179], v[212:215], v[64:67]
	v_mfma_f32_16x16x32_bf16 v[108:111], v[168:171], v[192:195], v[108:111]
	v_mfma_f32_16x16x32_bf16 v[104:107], v[180:183], v[192:195], v[104:107]
	v_mfma_f32_16x16x32_bf16 v[92:95], v[168:171], v[200:203], v[92:95]
	v_mfma_f32_16x16x32_bf16 v[88:91], v[180:183], v[200:203], v[88:91]
	v_mfma_f32_16x16x32_bf16 v[76:79], v[168:171], v[208:211], v[76:79]
	v_mfma_f32_16x16x32_bf16 v[72:75], v[180:183], v[208:211], v[72:75]
	v_mfma_f32_16x16x32_bf16 v[68:71], v[168:171], v[216:219], v[68:71]
	v_mfma_f32_16x16x32_bf16 v[64:67], v[180:183], v[216:219], v[64:67]
	s_setprio 0
	s_barrier
	s_mov_b32 m0, s55
	v_lshl_add_u64 v[172:173], s[20:21], 0, v[132:133]
	s_add_u32 s64, s20, 0x80000
	ds_read_b128 v[188:191], v144 offset:16384
	ds_read_b128 v[192:195], v144 offset:17408
	ds_read_b128 v[196:199], v144 offset:18432
	ds_read_b128 v[200:203], v144 offset:19456
	ds_read_b128 v[204:207], v144 offset:20480
	ds_read_b128 v[208:211], v144 offset:21504
	ds_read_b128 v[212:215], v144 offset:22528
	ds_read_b128 v[216:219], v144 offset:23552
	global_load_lds_dwordx4 v[172:173], off
	v_lshl_add_u64 v[184:185], s[20:21], 0, v[128:129]
	s_mov_b32 m0, s56
	s_addc_u32 s65, s21, 0
	global_load_lds_dwordx4 v[184:185], off
	v_lshl_add_u64 v[220:221], s[64:65], 0, v[132:133]
	s_mov_b32 m0, s57
	v_lshl_add_u64 v[222:223], s[22:23], 0, v[130:131]
	global_load_lds_dwordx4 v[220:221], off
	v_lshl_add_u64 v[220:221], s[64:65], 0, v[128:129]
	s_mov_b32 m0, s58
	s_nop 0
	global_load_lds_dwordx4 v[220:221], off
	v_lshl_add_u64 v[220:221], s[22:23], 0, v[134:135]
	s_mov_b32 m0, s1
	s_nop 0
	global_load_lds_dwordx4 v[220:221], off
	s_mov_b32 m0, s26
	s_nop 0
	global_load_lds_dwordx4 v[222:223], off
	s_waitcnt vmcnt(8)
	s_waitcnt lgkmcnt(0)
	s_barrier
	s_setprio 1
	s_waitcnt lgkmcnt(0)
	v_mfma_f32_16x16x32_bf16 v[60:63], v[148:151], v[188:191], v[60:63]
	v_mfma_f32_16x16x32_bf16 v[56:59], v[156:159], v[188:191], v[56:59]
	v_mfma_f32_16x16x32_bf16 v[52:55], v[148:151], v[196:199], v[52:55]
	v_mfma_f32_16x16x32_bf16 v[48:51], v[156:159], v[196:199], v[48:51]
	v_mfma_f32_16x16x32_bf16 v[36:39], v[148:151], v[204:207], v[36:39]
	v_mfma_f32_16x16x32_bf16 v[32:35], v[156:159], v[204:207], v[32:35]
	v_mfma_f32_16x16x32_bf16 v[20:23], v[148:151], v[212:215], v[20:23]
	v_mfma_f32_16x16x32_bf16 v[16:19], v[156:159], v[212:215], v[16:19]
	v_mfma_f32_16x16x32_bf16 v[60:63], v[152:155], v[192:195], v[60:63]
	v_mfma_f32_16x16x32_bf16 v[56:59], v[160:163], v[192:195], v[56:59]
	v_mfma_f32_16x16x32_bf16 v[52:55], v[152:155], v[200:203], v[52:55]
	v_mfma_f32_16x16x32_bf16 v[48:51], v[160:163], v[200:203], v[48:51]
	v_mfma_f32_16x16x32_bf16 v[36:39], v[152:155], v[208:211], v[36:39]
	v_mfma_f32_16x16x32_bf16 v[32:35], v[160:163], v[208:211], v[32:35]
	v_mfma_f32_16x16x32_bf16 v[20:23], v[152:155], v[216:219], v[20:23]
	v_mfma_f32_16x16x32_bf16 v[16:19], v[160:163], v[216:219], v[16:19]
	v_mfma_f32_16x16x32_bf16 v[44:47], v[164:167], v[188:191], v[44:47]
	v_mfma_f32_16x16x32_bf16 v[40:43], v[176:179], v[188:191], v[40:43]
	v_mfma_f32_16x16x32_bf16 v[28:31], v[164:167], v[196:199], v[28:31]
	v_mfma_f32_16x16x32_bf16 v[24:27], v[176:179], v[196:199], v[24:27]
	v_mfma_f32_16x16x32_bf16 v[12:15], v[164:167], v[204:207], v[12:15]
	v_mfma_f32_16x16x32_bf16 v[8:11], v[176:179], v[204:207], v[8:11]
	v_mfma_f32_16x16x32_bf16 v[4:7], v[164:167], v[212:215], v[4:7]
	v_mfma_f32_16x16x32_bf16 v[0:3], v[176:179], v[212:215], v[0:3]
	v_mfma_f32_16x16x32_bf16 v[44:47], v[168:171], v[192:195], v[44:47]
	v_mfma_f32_16x16x32_bf16 v[40:43], v[180:183], v[192:195], v[40:43]
	v_mfma_f32_16x16x32_bf16 v[28:31], v[168:171], v[200:203], v[28:31]
	v_mfma_f32_16x16x32_bf16 v[24:27], v[180:183], v[200:203], v[24:27]
	v_mfma_f32_16x16x32_bf16 v[12:15], v[168:171], v[208:211], v[12:15]
	v_mfma_f32_16x16x32_bf16 v[8:11], v[180:183], v[208:211], v[8:11]
	v_mfma_f32_16x16x32_bf16 v[4:7], v[168:171], v[216:219], v[4:7]
	v_mfma_f32_16x16x32_bf16 v[0:3], v[180:183], v[216:219], v[0:3]
	s_setprio 0
	s_barrier
	ds_read_b128 v[148:151], v145
	ds_read_b128 v[152:155], v145 offset:1024
	ds_read_b128 v[156:159], v145 offset:2048
	ds_read_b128 v[160:163], v145 offset:3072
	ds_read_b128 v[164:167], v146
	ds_read_b128 v[168:171], v146 offset:1024
	ds_read_b128 v[176:179], v146 offset:2048
	ds_read_b128 v[180:183], v146 offset:3072
	s_add_u32 s22, s22, 0xa0000
	s_addc_u32 s23, s23, 0
	s_mov_b32 m0, s27
	v_lshl_add_u64 v[224:225], s[22:23], 0, v[134:135]
	ds_read_b128 v[188:191], v144 offset:32768
	ds_read_b128 v[192:195], v144 offset:33792
	ds_read_b128 v[196:199], v144 offset:34816
	ds_read_b128 v[200:203], v144 offset:35840
	ds_read_b128 v[204:207], v144 offset:36864
	ds_read_b128 v[208:211], v144 offset:37888
	ds_read_b128 v[212:215], v144 offset:38912
	ds_read_b128 v[216:219], v144 offset:39936
	global_load_lds_dwordx4 v[224:225], off
	v_lshl_add_u64 v[224:225], s[22:23], 0, v[130:131]
	s_mov_b32 m0, s48
	s_nop 0
	global_load_lds_dwordx4 v[224:225], off
	s_waitcnt vmcnt(8)
	s_waitcnt lgkmcnt(0)
	s_barrier
	s_setprio 1
	s_waitcnt lgkmcnt(0)
	v_mfma_f32_16x16x32_bf16 v[124:127], v[148:151], v[188:191], v[124:127]
	v_mfma_f32_16x16x32_bf16 v[120:123], v[156:159], v[188:191], v[120:123]
	v_mfma_f32_16x16x32_bf16 v[116:119], v[148:151], v[196:199], v[116:119]
	v_mfma_f32_16x16x32_bf16 v[112:115], v[156:159], v[196:199], v[112:115]
	v_mfma_f32_16x16x32_bf16 v[100:103], v[148:151], v[204:207], v[100:103]
	v_mfma_f32_16x16x32_bf16 v[96:99], v[156:159], v[204:207], v[96:99]
	v_mfma_f32_16x16x32_bf16 v[84:87], v[148:151], v[212:215], v[84:87]
	v_mfma_f32_16x16x32_bf16 v[80:83], v[156:159], v[212:215], v[80:83]
	v_mfma_f32_16x16x32_bf16 v[124:127], v[152:155], v[192:195], v[124:127]
	v_mfma_f32_16x16x32_bf16 v[120:123], v[160:163], v[192:195], v[120:123]
	v_mfma_f32_16x16x32_bf16 v[116:119], v[152:155], v[200:203], v[116:119]
	v_mfma_f32_16x16x32_bf16 v[112:115], v[160:163], v[200:203], v[112:115]
	v_mfma_f32_16x16x32_bf16 v[100:103], v[152:155], v[208:211], v[100:103]
	v_mfma_f32_16x16x32_bf16 v[96:99], v[160:163], v[208:211], v[96:99]
	v_mfma_f32_16x16x32_bf16 v[84:87], v[152:155], v[216:219], v[84:87]
	v_mfma_f32_16x16x32_bf16 v[80:83], v[160:163], v[216:219], v[80:83]
	v_mfma_f32_16x16x32_bf16 v[108:111], v[164:167], v[188:191], v[108:111]
	v_mfma_f32_16x16x32_bf16 v[104:107], v[176:179], v[188:191], v[104:107]
	v_mfma_f32_16x16x32_bf16 v[92:95], v[164:167], v[196:199], v[92:95]
	v_mfma_f32_16x16x32_bf16 v[88:91], v[176:179], v[196:199], v[88:91]
	v_mfma_f32_16x16x32_bf16 v[76:79], v[164:167], v[204:207], v[76:79]
	v_mfma_f32_16x16x32_bf16 v[72:75], v[176:179], v[204:207], v[72:75]
	v_mfma_f32_16x16x32_bf16 v[68:71], v[164:167], v[212:215], v[68:71]
	v_mfma_f32_16x16x32_bf16 v[64:67], v[176:179], v[212:215], v[64:67]
	v_mfma_f32_16x16x32_bf16 v[108:111], v[168:171], v[192:195], v[108:111]
	v_mfma_f32_16x16x32_bf16 v[104:107], v[180:183], v[192:195], v[104:107]
	v_mfma_f32_16x16x32_bf16 v[92:95], v[168:171], v[200:203], v[92:95]
	v_mfma_f32_16x16x32_bf16 v[88:91], v[180:183], v[200:203], v[88:91]
	v_mfma_f32_16x16x32_bf16 v[76:79], v[168:171], v[208:211], v[76:79]
	v_mfma_f32_16x16x32_bf16 v[72:75], v[180:183], v[208:211], v[72:75]
	v_mfma_f32_16x16x32_bf16 v[68:71], v[168:171], v[216:219], v[68:71]
	v_mfma_f32_16x16x32_bf16 v[64:67], v[180:183], v[216:219], v[64:67]
	s_setprio 0
	s_barrier
	s_mov_b32 m0, s59
	v_lshl_add_u64 v[172:173], v[172:173], 0, s[14:15]
	s_add_u32 s20, s20, 0x80080
	ds_read_b128 v[188:191], v144 offset:49152
	ds_read_b128 v[192:195], v144 offset:50176
	ds_read_b128 v[196:199], v144 offset:51200
	ds_read_b128 v[200:203], v144 offset:52224
	ds_read_b128 v[204:207], v144 offset:53248
	ds_read_b128 v[208:211], v144 offset:54272
	ds_read_b128 v[212:215], v144 offset:55296
	ds_read_b128 v[216:219], v144 offset:56320
	global_load_lds_dwordx4 v[172:173], off
	v_lshl_add_u64 v[172:173], v[184:185], 0, s[14:15]
	s_mov_b32 m0, s60
	s_addc_u32 s21, s21, 0
	global_load_lds_dwordx4 v[172:173], off
	v_lshl_add_u64 v[172:173], s[20:21], 0, v[132:133]
	s_mov_b32 m0, s61
	s_nop 0
	global_load_lds_dwordx4 v[172:173], off
	v_lshl_add_u64 v[172:173], s[20:21], 0, v[128:129]
	s_mov_b32 m0, s62
	s_nop 0
	global_load_lds_dwordx4 v[172:173], off
	v_lshl_add_u64 v[172:173], v[220:221], 0, s[14:15]
	s_mov_b32 m0, s50
	s_nop 0
	global_load_lds_dwordx4 v[172:173], off
	v_lshl_add_u64 v[172:173], v[222:223], 0, s[14:15]
	s_mov_b32 m0, s51
	s_nop 0
	global_load_lds_dwordx4 v[172:173], off
	s_waitcnt vmcnt(8)
	s_waitcnt lgkmcnt(0)
	s_barrier
	s_setprio 1
	s_waitcnt lgkmcnt(0)
	v_mfma_f32_16x16x32_bf16 v[60:63], v[148:151], v[188:191], v[60:63]
	v_mfma_f32_16x16x32_bf16 v[56:59], v[156:159], v[188:191], v[56:59]
	v_mfma_f32_16x16x32_bf16 v[52:55], v[148:151], v[196:199], v[52:55]
	v_mfma_f32_16x16x32_bf16 v[48:51], v[156:159], v[196:199], v[48:51]
	v_mfma_f32_16x16x32_bf16 v[36:39], v[148:151], v[204:207], v[36:39]
	v_mfma_f32_16x16x32_bf16 v[32:35], v[156:159], v[204:207], v[32:35]
	v_mfma_f32_16x16x32_bf16 v[20:23], v[148:151], v[212:215], v[20:23]
	v_mfma_f32_16x16x32_bf16 v[16:19], v[156:159], v[212:215], v[16:19]
	v_mfma_f32_16x16x32_bf16 v[60:63], v[152:155], v[192:195], v[60:63]
	v_mfma_f32_16x16x32_bf16 v[56:59], v[160:163], v[192:195], v[56:59]
	v_mfma_f32_16x16x32_bf16 v[52:55], v[152:155], v[200:203], v[52:55]
	v_mfma_f32_16x16x32_bf16 v[48:51], v[160:163], v[200:203], v[48:51]
	v_mfma_f32_16x16x32_bf16 v[36:39], v[152:155], v[208:211], v[36:39]
	v_mfma_f32_16x16x32_bf16 v[32:35], v[160:163], v[208:211], v[32:35]
	v_mfma_f32_16x16x32_bf16 v[20:23], v[152:155], v[216:219], v[20:23]
	v_mfma_f32_16x16x32_bf16 v[16:19], v[160:163], v[216:219], v[16:19]
	v_mfma_f32_16x16x32_bf16 v[44:47], v[164:167], v[188:191], v[44:47]
	v_mfma_f32_16x16x32_bf16 v[40:43], v[176:179], v[188:191], v[40:43]
	v_mfma_f32_16x16x32_bf16 v[28:31], v[164:167], v[196:199], v[28:31]
	v_mfma_f32_16x16x32_bf16 v[24:27], v[176:179], v[196:199], v[24:27]
	v_mfma_f32_16x16x32_bf16 v[12:15], v[164:167], v[204:207], v[12:15]
	v_mfma_f32_16x16x32_bf16 v[8:11], v[176:179], v[204:207], v[8:11]
	v_mfma_f32_16x16x32_bf16 v[4:7], v[164:167], v[212:215], v[4:7]
	v_mfma_f32_16x16x32_bf16 v[0:3], v[176:179], v[212:215], v[0:3]
	v_mfma_f32_16x16x32_bf16 v[44:47], v[168:171], v[192:195], v[44:47]
	v_mfma_f32_16x16x32_bf16 v[40:43], v[180:183], v[192:195], v[40:43]
	v_mfma_f32_16x16x32_bf16 v[28:31], v[168:171], v[200:203], v[28:31]
	v_mfma_f32_16x16x32_bf16 v[24:27], v[180:183], v[200:203], v[24:27]
	v_mfma_f32_16x16x32_bf16 v[12:15], v[168:171], v[208:211], v[12:15]
	v_mfma_f32_16x16x32_bf16 v[8:11], v[180:183], v[208:211], v[8:11]
	v_mfma_f32_16x16x32_bf16 v[4:7], v[168:171], v[216:219], v[4:7]
	v_mfma_f32_16x16x32_bf16 v[0:3], v[180:183], v[216:219], v[0:3]
	s_setprio 0
	s_barrier
	s_add_i32 s52, s52, 2
	s_add_u32 s18, s18, 0x100
	s_addc_u32 s19, s19, 0
	s_cmp_gt_u32 s52, 29
	s_cbranch_scc0 .LBB0_250
	s_cmpk_lt_u32 s24, 0x100
	s_cbranch_scc0 .LBB0_253
	s_barrier

.LBB0_599:
	v_add_u32_e32 v1, s79, v173
	s_add_i32 s2, s64, 2
	ds_read_b128 v[132:135], v1
	ds_read_b128 v[136:139], v1 offset:1024
	ds_read_b128 v[140:143], v1 offset:2048
	ds_read_b128 v[178:181], v1 offset:3072
	v_add_u32_e32 v1, s80, v173
	s_add_u32 s65, s58, s60
	ds_read_b128 v[182:185], v1
	ds_read_b128 v[188:191], v1 offset:1024
	ds_read_b128 v[192:195], v1 offset:2048
	ds_read_b128 v[196:199], v1 offset:3072
	s_addc_u32 s66, s59, s61
	s_add_u32 s65, s65, 0x100
	s_addc_u32 s66, s66, 0
	s_add_u32 s75, s89, s60
	s_addc_u32 s91, s90, s61
	s_cmp_eq_u32 s7, s64
	s_cselect_b32 s67, s51, s66
	s_cselect_b32 s66, s50, s65
	s_cselect_b32 s65, s53, s91
	s_cselect_b32 s64, s52, s75
	v_lshl_add_u64 v[2:3], v[168:169], 0, s[60:61]
	s_add_i32 m0, s69, 0xc000
	ds_read_b128 v[200:203], v174
	ds_read_b128 v[204:207], v174 offset:1024
	ds_read_b128 v[208:211], v174 offset:2048
	ds_read_b128 v[212:215], v174 offset:3072
	ds_read_b128 v[216:219], v174 offset:4096
	ds_read_b128 v[220:223], v174 offset:5120
	ds_read_b128 v[224:227], v174 offset:6144
	ds_read_b128 v[228:231], v174 offset:7168
	global_load_lds_dwordx4 v[2:3], off
	v_lshl_add_u64 v[2:3], v[170:171], 0, s[60:61]
	s_add_i32 m0, s69, 0xe000
	s_nop 0
	global_load_lds_dwordx4 v[2:3], off
	s_waitcnt vmcnt(8)
	s_waitcnt lgkmcnt(0)
	s_barrier
	s_setprio 1
	s_waitcnt lgkmcnt(0)
	v_mfma_f32_16x16x32_bf16 v[128:131], v[132:135], v[200:203], v[128:131]
	v_mfma_f32_16x16x32_bf16 v[124:127], v[140:143], v[200:203], v[124:127]
	v_mfma_f32_16x16x32_bf16 v[112:115], v[132:135], v[208:211], v[112:115]
	v_mfma_f32_16x16x32_bf16 v[108:111], v[140:143], v[208:211], v[108:111]
	v_mfma_f32_16x16x32_bf16 v[96:99], v[132:135], v[216:219], v[96:99]
	v_mfma_f32_16x16x32_bf16 v[92:95], v[140:143], v[216:219], v[92:95]
	v_mfma_f32_16x16x32_bf16 v[80:83], v[132:135], v[224:227], v[80:83]
	v_mfma_f32_16x16x32_bf16 v[76:79], v[140:143], v[224:227], v[76:79]
	v_mfma_f32_16x16x32_bf16 v[128:131], v[136:139], v[204:207], v[128:131]
	v_mfma_f32_16x16x32_bf16 v[124:127], v[178:181], v[204:207], v[124:127]
	v_mfma_f32_16x16x32_bf16 v[112:115], v[136:139], v[212:215], v[112:115]
	v_mfma_f32_16x16x32_bf16 v[108:111], v[178:181], v[212:215], v[108:111]
	v_mfma_f32_16x16x32_bf16 v[96:99], v[136:139], v[220:223], v[96:99]
	v_mfma_f32_16x16x32_bf16 v[92:95], v[178:181], v[220:223], v[92:95]
	v_mfma_f32_16x16x32_bf16 v[80:83], v[136:139], v[228:231], v[80:83]
	v_mfma_f32_16x16x32_bf16 v[76:79], v[178:181], v[228:231], v[76:79]
	v_mfma_f32_16x16x32_bf16 v[120:123], v[182:185], v[200:203], v[120:123]
	v_mfma_f32_16x16x32_bf16 v[116:119], v[192:195], v[200:203], v[116:119]
	v_mfma_f32_16x16x32_bf16 v[104:107], v[182:185], v[208:211], v[104:107]
	v_mfma_f32_16x16x32_bf16 v[100:103], v[192:195], v[208:211], v[100:103]
	v_mfma_f32_16x16x32_bf16 v[88:91], v[182:185], v[216:219], v[88:91]
	v_mfma_f32_16x16x32_bf16 v[84:87], v[192:195], v[216:219], v[84:87]
	v_mfma_f32_16x16x32_bf16 v[72:75], v[182:185], v[224:227], v[72:75]
	v_mfma_f32_16x16x32_bf16 v[68:71], v[192:195], v[224:227], v[68:71]
	v_mfma_f32_16x16x32_bf16 v[120:123], v[188:191], v[204:207], v[120:123]
	v_mfma_f32_16x16x32_bf16 v[116:119], v[196:199], v[204:207], v[116:119]
	v_mfma_f32_16x16x32_bf16 v[104:107], v[188:191], v[212:215], v[104:107]
	v_mfma_f32_16x16x32_bf16 v[100:103], v[196:199], v[212:215], v[100:103]
	v_mfma_f32_16x16x32_bf16 v[88:91], v[188:191], v[220:223], v[88:91]
	v_mfma_f32_16x16x32_bf16 v[84:87], v[196:199], v[220:223], v[84:87]
	v_mfma_f32_16x16x32_bf16 v[72:75], v[188:191], v[228:231], v[72:75]
	v_mfma_f32_16x16x32_bf16 v[68:71], v[196:199], v[228:231], v[68:71]
	s_setprio 0
	s_barrier
	s_add_i32 s75, s79, s68
	v_lshl_add_u64 v[232:233], s[64:65], 0, v[148:149]
	s_mov_b32 m0, s75
	ds_read_b128 v[200:203], v174 offset:16384
	ds_read_b128 v[204:207], v174 offset:17408
	ds_read_b128 v[208:211], v174 offset:18432
	ds_read_b128 v[212:215], v174 offset:19456
	ds_read_b128 v[216:219], v174 offset:20480
	ds_read_b128 v[220:223], v174 offset:21504
	ds_read_b128 v[224:227], v174 offset:22528
	ds_read_b128 v[228:231], v174 offset:23552
	global_load_lds_dwordx4 v[232:233], off
	s_add_i32 m0, s75, 0x2000
	s_add_u32 s92, s64, 0xa0000
	v_lshl_add_u64 v[234:235], s[64:65], 0, v[144:145]
	s_addc_u32 s93, s65, 0
	s_add_i32 s75, s80, s68
	global_load_lds_dwordx4 v[234:235], off
	v_lshl_add_u64 v[2:3], s[92:93], 0, v[148:149]
	s_mov_b32 m0, s75
	v_lshl_add_u64 v[236:237], s[66:67], 0, v[150:151]
	global_load_lds_dwordx4 v[2:3], off
	v_lshl_add_u64 v[2:3], s[92:93], 0, v[144:145]
	s_add_i32 m0, s75, 0x2000
	v_lshl_add_u64 v[238:239], s[66:67], 0, v[146:147]
	global_load_lds_dwordx4 v[2:3], off
	s_mov_b32 m0, s69
	s_nop 0
	global_load_lds_dwordx4 v[236:237], off
	s_mov_b32 m0, s70
	s_nop 0
	global_load_lds_dwordx4 v[238:239], off
	s_waitcnt vmcnt(8)
	s_waitcnt lgkmcnt(0)
	s_barrier
	s_setprio 1
	s_waitcnt lgkmcnt(0)
	v_mfma_f32_16x16x32_bf16 v[64:67], v[132:135], v[200:203], v[64:67]
	v_mfma_f32_16x16x32_bf16 v[60:63], v[140:143], v[200:203], v[60:63]
	v_mfma_f32_16x16x32_bf16 v[48:51], v[132:135], v[208:211], v[48:51]
	v_mfma_f32_16x16x32_bf16 v[44:47], v[140:143], v[208:211], v[44:47]
	v_mfma_f32_16x16x32_bf16 v[32:35], v[132:135], v[216:219], v[32:35]
	v_mfma_f32_16x16x32_bf16 v[28:31], v[140:143], v[216:219], v[28:31]
	v_mfma_f32_16x16x32_bf16 v[16:19], v[132:135], v[224:227], v[16:19]
	v_mfma_f32_16x16x32_bf16 v[12:15], v[140:143], v[224:227], v[12:15]
	v_mfma_f32_16x16x32_bf16 v[64:67], v[136:139], v[204:207], v[64:67]
	v_mfma_f32_16x16x32_bf16 v[60:63], v[178:181], v[204:207], v[60:63]
	v_mfma_f32_16x16x32_bf16 v[48:51], v[136:139], v[212:215], v[48:51]
	v_mfma_f32_16x16x32_bf16 v[44:47], v[178:181], v[212:215], v[44:47]
	v_mfma_f32_16x16x32_bf16 v[32:35], v[136:139], v[220:223], v[32:35]
	v_mfma_f32_16x16x32_bf16 v[28:31], v[178:181], v[220:223], v[28:31]
	v_mfma_f32_16x16x32_bf16 v[16:19], v[136:139], v[228:231], v[16:19]
	v_mfma_f32_16x16x32_bf16 v[12:15], v[178:181], v[228:231], v[12:15]
	v_mfma_f32_16x16x32_bf16 v[56:59], v[182:185], v[200:203], v[56:59]
	v_mfma_f32_16x16x32_bf16 v[52:55], v[192:195], v[200:203], v[52:55]
	v_mfma_f32_16x16x32_bf16 v[40:43], v[182:185], v[208:211], v[40:43]
	v_mfma_f32_16x16x32_bf16 v[36:39], v[192:195], v[208:211], v[36:39]
	v_mfma_f32_16x16x32_bf16 v[24:27], v[182:185], v[216:219], v[24:27]
	v_mfma_f32_16x16x32_bf16 v[20:23], v[192:195], v[216:219], v[20:23]
	v_mfma_f32_16x16x32_bf16 v[8:11], v[182:185], v[224:227], v[8:11]
	v_mfma_f32_16x16x32_bf16 v[2:5], v[192:195], v[224:227], v[4:7]
	v_mfma_f32_16x16x32_bf16 v[56:59], v[188:191], v[204:207], v[56:59]
	v_mfma_f32_16x16x32_bf16 v[52:55], v[196:199], v[204:207], v[52:55]
	v_mfma_f32_16x16x32_bf16 v[40:43], v[188:191], v[212:215], v[40:43]
	v_mfma_f32_16x16x32_bf16 v[36:39], v[196:199], v[212:215], v[36:39]
	v_mfma_f32_16x16x32_bf16 v[24:27], v[188:191], v[220:223], v[24:27]
	v_mfma_f32_16x16x32_bf16 v[20:23], v[196:199], v[220:223], v[20:23]
	v_mfma_f32_16x16x32_bf16 v[8:11], v[188:191], v[228:231], v[8:11]
	v_mfma_f32_16x16x32_bf16 v[2:5], v[196:199], v[228:231], v[2:5]
	s_setprio 0
	s_barrier
	s_add_i32 s75, 0, 0x18000
	v_add_u32_e32 v1, s75, v173
	s_add_i32 s91, 0, 0x1c000
	ds_read_b128 v[132:135], v1
	ds_read_b128 v[136:139], v1 offset:1024
	ds_read_b128 v[140:143], v1 offset:2048
	ds_read_b128 v[178:181], v1 offset:3072
	v_add_u32_e32 v1, s91, v173
	ds_read_b128 v[182:185], v1
	ds_read_b128 v[188:191], v1 offset:1024
	ds_read_b128 v[192:195], v1 offset:2048
	ds_read_b128 v[196:199], v1 offset:3072
	s_add_u32 s66, s66, 0xa0000
	s_addc_u32 s67, s67, 0
	s_mov_b32 m0, s71
	v_lshl_add_u64 v[6:7], s[66:67], 0, v[150:151]
	ds_read_b128 v[200:203], v174 offset:32768
	ds_read_b128 v[204:207], v174 offset:33792
	ds_read_b128 v[208:211], v174 offset:34816
	ds_read_b128 v[212:215], v174 offset:35840
	ds_read_b128 v[216:219], v174 offset:36864
	ds_read_b128 v[220:223], v174 offset:37888
	ds_read_b128 v[224:227], v174 offset:38912
	ds_read_b128 v[228:231], v174 offset:39936
	global_load_lds_dwordx4 v[6:7], off
	v_lshl_add_u64 v[6:7], s[66:67], 0, v[146:147]
	s_mov_b32 m0, s72
	s_nop 0
	global_load_lds_dwordx4 v[6:7], off
	s_waitcnt vmcnt(8)
	s_waitcnt lgkmcnt(0)
	s_barrier
	s_setprio 1
	s_waitcnt lgkmcnt(0)
	v_mfma_f32_16x16x32_bf16 v[128:131], v[132:135], v[200:203], v[128:131]
	v_mfma_f32_16x16x32_bf16 v[124:127], v[140:143], v[200:203], v[124:127]
	v_mfma_f32_16x16x32_bf16 v[112:115], v[132:135], v[208:211], v[112:115]
	v_mfma_f32_16x16x32_bf16 v[108:111], v[140:143], v[208:211], v[108:111]
	v_mfma_f32_16x16x32_bf16 v[96:99], v[132:135], v[216:219], v[96:99]
	v_mfma_f32_16x16x32_bf16 v[92:95], v[140:143], v[216:219], v[92:95]
	v_mfma_f32_16x16x32_bf16 v[80:83], v[132:135], v[224:227], v[80:83]
	v_mfma_f32_16x16x32_bf16 v[76:79], v[140:143], v[224:227], v[76:79]
	v_mfma_f32_16x16x32_bf16 v[128:131], v[136:139], v[204:207], v[128:131]
	v_mfma_f32_16x16x32_bf16 v[124:127], v[178:181], v[204:207], v[124:127]
	v_mfma_f32_16x16x32_bf16 v[112:115], v[136:139], v[212:215], v[112:115]
	v_mfma_f32_16x16x32_bf16 v[108:111], v[178:181], v[212:215], v[108:111]
	v_mfma_f32_16x16x32_bf16 v[96:99], v[136:139], v[220:223], v[96:99]
	v_mfma_f32_16x16x32_bf16 v[92:95], v[178:181], v[220:223], v[92:95]
	v_mfma_f32_16x16x32_bf16 v[80:83], v[136:139], v[228:231], v[80:83]
	v_mfma_f32_16x16x32_bf16 v[76:79], v[178:181], v[228:231], v[76:79]
	v_mfma_f32_16x16x32_bf16 v[120:123], v[182:185], v[200:203], v[120:123]
	v_mfma_f32_16x16x32_bf16 v[116:119], v[192:195], v[200:203], v[116:119]
	v_mfma_f32_16x16x32_bf16 v[104:107], v[182:185], v[208:211], v[104:107]
	v_mfma_f32_16x16x32_bf16 v[100:103], v[192:195], v[208:211], v[100:103]
	v_mfma_f32_16x16x32_bf16 v[88:91], v[182:185], v[216:219], v[88:91]
	v_mfma_f32_16x16x32_bf16 v[84:87], v[192:195], v[216:219], v[84:87]
	v_mfma_f32_16x16x32_bf16 v[72:75], v[182:185], v[224:227], v[72:75]
	v_mfma_f32_16x16x32_bf16 v[68:71], v[192:195], v[224:227], v[68:71]
	v_mfma_f32_16x16x32_bf16 v[120:123], v[188:191], v[204:207], v[120:123]
	v_mfma_f32_16x16x32_bf16 v[116:119], v[196:199], v[204:207], v[116:119]
	v_mfma_f32_16x16x32_bf16 v[104:107], v[188:191], v[212:215], v[104:107]
	v_mfma_f32_16x16x32_bf16 v[100:103], v[196:199], v[212:215], v[100:103]
	v_mfma_f32_16x16x32_bf16 v[88:91], v[188:191], v[220:223], v[88:91]
	v_mfma_f32_16x16x32_bf16 v[84:87], v[196:199], v[220:223], v[84:87]
	v_mfma_f32_16x16x32_bf16 v[72:75], v[188:191], v[228:231], v[72:75]
	v_mfma_f32_16x16x32_bf16 v[68:71], v[196:199], v[228:231], v[68:71]
	s_setprio 0
	s_barrier
	s_add_i32 s66, s75, s68
	v_lshl_add_u64 v[6:7], v[232:233], 0, s[14:15]
	s_mov_b32 m0, s66
	ds_read_b128 v[200:203], v174 offset:49152
	ds_read_b128 v[204:207], v174 offset:50176
	ds_read_b128 v[208:211], v174 offset:51200
	ds_read_b128 v[212:215], v174 offset:52224
	ds_read_b128 v[216:219], v174 offset:53248
	ds_read_b128 v[220:223], v174 offset:54272
	ds_read_b128 v[224:227], v174 offset:55296
	ds_read_b128 v[228:231], v174 offset:56320
	global_load_lds_dwordx4 v[6:7], off
	s_add_i32 m0, s66, 0x2000
	s_add_u32 s64, s64, 0xa0080
	v_lshl_add_u64 v[6:7], v[234:235], 0, s[14:15]
	s_addc_u32 s65, s65, 0
	s_add_i32 s66, s91, s68
	global_load_lds_dwordx4 v[6:7], off
	v_lshl_add_u64 v[6:7], s[64:65], 0, v[148:149]
	s_mov_b32 m0, s66
	s_nop 0
	global_load_lds_dwordx4 v[6:7], off
	v_lshl_add_u64 v[6:7], s[64:65], 0, v[144:145]
	s_add_i32 m0, s66, 0x2000
	s_nop 0
	global_load_lds_dwordx4 v[6:7], off
	v_lshl_add_u64 v[6:7], v[236:237], 0, s[14:15]
	s_mov_b32 m0, s73
	s_nop 0
	global_load_lds_dwordx4 v[6:7], off
	v_lshl_add_u64 v[6:7], v[238:239], 0, s[14:15]
	s_mov_b32 m0, s76
	s_nop 0
	global_load_lds_dwordx4 v[6:7], off
	s_waitcnt vmcnt(8)
	s_waitcnt lgkmcnt(0)
	s_barrier
	s_setprio 1
	s_waitcnt lgkmcnt(0)
	v_mfma_f32_16x16x32_bf16 v[64:67], v[132:135], v[200:203], v[64:67]
	v_mfma_f32_16x16x32_bf16 v[60:63], v[140:143], v[200:203], v[60:63]
	v_mfma_f32_16x16x32_bf16 v[48:51], v[132:135], v[208:211], v[48:51]
	v_mfma_f32_16x16x32_bf16 v[44:47], v[140:143], v[208:211], v[44:47]
	v_mfma_f32_16x16x32_bf16 v[32:35], v[132:135], v[216:219], v[32:35]
	v_mfma_f32_16x16x32_bf16 v[28:31], v[140:143], v[216:219], v[28:31]
	v_mfma_f32_16x16x32_bf16 v[16:19], v[132:135], v[224:227], v[16:19]
	v_mfma_f32_16x16x32_bf16 v[12:15], v[140:143], v[224:227], v[12:15]
	v_mfma_f32_16x16x32_bf16 v[64:67], v[136:139], v[204:207], v[64:67]
	v_mfma_f32_16x16x32_bf16 v[60:63], v[178:181], v[204:207], v[60:63]
	v_mfma_f32_16x16x32_bf16 v[48:51], v[136:139], v[212:215], v[48:51]
	v_mfma_f32_16x16x32_bf16 v[44:47], v[178:181], v[212:215], v[44:47]
	v_mfma_f32_16x16x32_bf16 v[32:35], v[136:139], v[220:223], v[32:35]
	v_mfma_f32_16x16x32_bf16 v[28:31], v[178:181], v[220:223], v[28:31]
	v_mfma_f32_16x16x32_bf16 v[16:19], v[136:139], v[228:231], v[16:19]
	v_mfma_f32_16x16x32_bf16 v[12:15], v[178:181], v[228:231], v[12:15]
	v_mfma_f32_16x16x32_bf16 v[56:59], v[182:185], v[200:203], v[56:59]
	v_mfma_f32_16x16x32_bf16 v[52:55], v[192:195], v[200:203], v[52:55]
	v_mfma_f32_16x16x32_bf16 v[40:43], v[182:185], v[208:211], v[40:43]
	v_mfma_f32_16x16x32_bf16 v[36:39], v[192:195], v[208:211], v[36:39]
	v_mfma_f32_16x16x32_bf16 v[24:27], v[182:185], v[216:219], v[24:27]
	v_mfma_f32_16x16x32_bf16 v[20:23], v[192:195], v[216:219], v[20:23]
	v_mfma_f32_16x16x32_bf16 v[6:9], v[182:185], v[224:227], v[8:11]
	v_mfma_f32_16x16x32_bf16 v[2:5], v[192:195], v[224:227], v[2:5]
	v_mfma_f32_16x16x32_bf16 v[56:59], v[188:191], v[204:207], v[56:59]
	v_mfma_f32_16x16x32_bf16 v[52:55], v[196:199], v[204:207], v[52:55]
	v_mfma_f32_16x16x32_bf16 v[40:43], v[188:191], v[212:215], v[40:43]
	v_mfma_f32_16x16x32_bf16 v[36:39], v[196:199], v[212:215], v[36:39]
	v_mfma_f32_16x16x32_bf16 v[24:27], v[188:191], v[220:223], v[24:27]
	v_mfma_f32_16x16x32_bf16 v[20:23], v[196:199], v[220:223], v[20:23]
	v_mfma_f32_16x16x32_bf16 v[8:11], v[188:191], v[228:231], v[6:9]
	v_mfma_f32_16x16x32_bf16 v[4:7], v[196:199], v[228:231], v[2:5]
	s_setprio 0
	s_and_b64 vcc, exec, s[18:19]
	s_cbranch_vccnz .Lhk_skipB
	s_and_b64 vcc, exec, s[62:63]
	s_cbranch_vccnz .Lhk_skipB
	s_cmp_eq_u32 s2, 16
	s_cbranch_scc1 .Lhk_doB
	s_cmp_eq_u32 s2, 24
	s_cbranch_scc0 .Lhk_skipB

.LBB0_672:
	ds_read_b128 v[128:131], v185
	ds_read_b128 v[132:135], v185 offset:1024
	ds_read_b128 v[136:139], v185 offset:2048
	ds_read_b128 v[140:143], v185 offset:3072
	ds_read_b128 v[162:165], v186
	ds_read_b128 v[166:169], v186 offset:1024
	ds_read_b128 v[170:173], v186 offset:2048
	ds_read_b128 v[174:177], v186 offset:3072
	s_add_u32 s38, s6, 0xfff80080
	s_addc_u32 s39, s7, -1
	s_cmp_eq_u32 s56, 28
	s_cselect_b32 s41, s27, s39
	s_cselect_b32 s40, s26, s38
	s_cselect_b32 s39, s23, s25
	s_cselect_b32 s38, s22, s5
	v_lshl_add_u64 v[182:183], s[6:7], 0, v[158:159]
	s_add_i32 m0, s42, 0xc000
	ds_read_b128 v[178:181], v188
	ds_read_b128 v[192:195], v188 offset:1024
	ds_read_b128 v[196:199], v188 offset:2048
	ds_read_b128 v[200:203], v188 offset:3072
	ds_read_b128 v[204:207], v188 offset:4096
	ds_read_b128 v[208:211], v188 offset:5120
	ds_read_b128 v[212:215], v188 offset:6144
	ds_read_b128 v[216:219], v188 offset:7168
	global_load_lds_dwordx4 v[182:183], off
	v_lshl_add_u64 v[182:183], s[6:7], 0, v[160:161]
	s_add_i32 m0, s42, 0xe000
	s_nop 0
	global_load_lds_dwordx4 v[182:183], off
	s_waitcnt vmcnt(8)
	s_waitcnt lgkmcnt(0)
	s_barrier
	s_setprio 1
	s_waitcnt lgkmcnt(0)
	v_mfma_f32_16x16x32_bf16 v[124:127], v[128:131], v[178:181], v[124:127]
	v_mfma_f32_16x16x32_bf16 v[120:123], v[136:139], v[178:181], v[120:123]
	v_mfma_f32_16x16x32_bf16 v[108:111], v[128:131], v[196:199], v[108:111]
	v_mfma_f32_16x16x32_bf16 v[104:107], v[136:139], v[196:199], v[104:107]
	v_mfma_f32_16x16x32_bf16 v[92:95], v[128:131], v[204:207], v[92:95]
	v_mfma_f32_16x16x32_bf16 v[88:91], v[136:139], v[204:207], v[88:91]
	v_mfma_f32_16x16x32_bf16 v[76:79], v[128:131], v[212:215], v[76:79]
	v_mfma_f32_16x16x32_bf16 v[72:75], v[136:139], v[212:215], v[72:75]
	v_mfma_f32_16x16x32_bf16 v[124:127], v[132:135], v[192:195], v[124:127]
	v_mfma_f32_16x16x32_bf16 v[120:123], v[140:143], v[192:195], v[120:123]
	v_mfma_f32_16x16x32_bf16 v[108:111], v[132:135], v[200:203], v[108:111]
	v_mfma_f32_16x16x32_bf16 v[104:107], v[140:143], v[200:203], v[104:107]
	v_mfma_f32_16x16x32_bf16 v[92:95], v[132:135], v[208:211], v[92:95]
	v_mfma_f32_16x16x32_bf16 v[88:91], v[140:143], v[208:211], v[88:91]
	v_mfma_f32_16x16x32_bf16 v[76:79], v[132:135], v[216:219], v[76:79]
	v_mfma_f32_16x16x32_bf16 v[72:75], v[140:143], v[216:219], v[72:75]
	v_mfma_f32_16x16x32_bf16 v[116:119], v[162:165], v[178:181], v[116:119]
	v_mfma_f32_16x16x32_bf16 v[112:115], v[170:173], v[178:181], v[112:115]
	v_mfma_f32_16x16x32_bf16 v[100:103], v[162:165], v[196:199], v[100:103]
	v_mfma_f32_16x16x32_bf16 v[96:99], v[170:173], v[196:199], v[96:99]
	v_mfma_f32_16x16x32_bf16 v[84:87], v[162:165], v[204:207], v[84:87]
	v_mfma_f32_16x16x32_bf16 v[80:83], v[170:173], v[204:207], v[80:83]
	v_mfma_f32_16x16x32_bf16 v[68:71], v[162:165], v[212:215], v[68:71]
	v_mfma_f32_16x16x32_bf16 v[64:67], v[170:173], v[212:215], v[64:67]
	v_mfma_f32_16x16x32_bf16 v[116:119], v[166:169], v[192:195], v[116:119]
	v_mfma_f32_16x16x32_bf16 v[112:115], v[174:177], v[192:195], v[112:115]
	v_mfma_f32_16x16x32_bf16 v[100:103], v[166:169], v[200:203], v[100:103]
	v_mfma_f32_16x16x32_bf16 v[96:99], v[174:177], v[200:203], v[96:99]
	v_mfma_f32_16x16x32_bf16 v[84:87], v[166:169], v[208:211], v[84:87]
	v_mfma_f32_16x16x32_bf16 v[80:83], v[174:177], v[208:211], v[80:83]
	v_mfma_f32_16x16x32_bf16 v[68:71], v[166:169], v[216:219], v[68:71]
	v_mfma_f32_16x16x32_bf16 v[64:67], v[174:177], v[216:219], v[64:67]
	s_setprio 0
	s_barrier
	s_add_i32 s57, s51, s35
	v_lshl_add_u64 v[182:183], s[38:39], 0, v[148:149]
	s_mov_b32 m0, s57
	ds_read_b128 v[178:181], v188 offset:16384
	ds_read_b128 v[192:195], v188 offset:17408
	ds_read_b128 v[196:199], v188 offset:18432
	ds_read_b128 v[200:203], v188 offset:19456
	ds_read_b128 v[204:207], v188 offset:20480
	ds_read_b128 v[208:211], v188 offset:21504
	ds_read_b128 v[212:215], v188 offset:22528
	ds_read_b128 v[216:219], v188 offset:23552
	global_load_lds_dwordx4 v[182:183], off
	s_add_i32 m0, s57, 0x2000
	s_add_u32 s58, s38, 0x80000
	v_lshl_add_u64 v[220:221], s[38:39], 0, v[144:145]
	s_addc_u32 s59, s39, 0
	s_add_i32 s57, s52, s35
	global_load_lds_dwordx4 v[220:221], off
	v_lshl_add_u64 v[222:223], s[58:59], 0, v[148:149]
	s_mov_b32 m0, s57
	v_lshl_add_u64 v[224:225], s[40:41], 0, v[146:147]
	global_load_lds_dwordx4 v[222:223], off
	v_lshl_add_u64 v[222:223], s[58:59], 0, v[144:145]
	s_add_i32 m0, s57, 0x2000
	s_nop 0
	global_load_lds_dwordx4 v[222:223], off
	v_lshl_add_u64 v[222:223], s[40:41], 0, v[150:151]
	s_mov_b32 m0, s42
	s_nop 0
	global_load_lds_dwordx4 v[222:223], off
	s_mov_b32 m0, s43
	s_nop 0
	global_load_lds_dwordx4 v[224:225], off
	s_waitcnt vmcnt(8)
	s_waitcnt lgkmcnt(0)
	s_barrier
	s_setprio 1
	s_waitcnt lgkmcnt(0)
	v_mfma_f32_16x16x32_bf16 v[60:63], v[128:131], v[178:181], v[60:63]
	v_mfma_f32_16x16x32_bf16 v[56:59], v[136:139], v[178:181], v[56:59]
	v_mfma_f32_16x16x32_bf16 v[44:47], v[128:131], v[196:199], v[44:47]
	v_mfma_f32_16x16x32_bf16 v[40:43], v[136:139], v[196:199], v[40:43]
	v_mfma_f32_16x16x32_bf16 v[28:31], v[128:131], v[204:207], v[28:31]
	v_mfma_f32_16x16x32_bf16 v[24:27], v[136:139], v[204:207], v[24:27]
	v_mfma_f32_16x16x32_bf16 v[12:15], v[128:131], v[212:215], v[12:15]
	v_mfma_f32_16x16x32_bf16 v[8:11], v[136:139], v[212:215], v[8:11]
	v_mfma_f32_16x16x32_bf16 v[60:63], v[132:135], v[192:195], v[60:63]
	v_mfma_f32_16x16x32_bf16 v[56:59], v[140:143], v[192:195], v[56:59]
	v_mfma_f32_16x16x32_bf16 v[44:47], v[132:135], v[200:203], v[44:47]
	v_mfma_f32_16x16x32_bf16 v[40:43], v[140:143], v[200:203], v[40:43]
	v_mfma_f32_16x16x32_bf16 v[28:31], v[132:135], v[208:211], v[28:31]
	v_mfma_f32_16x16x32_bf16 v[24:27], v[140:143], v[208:211], v[24:27]
	v_mfma_f32_16x16x32_bf16 v[12:15], v[132:135], v[216:219], v[12:15]
	v_mfma_f32_16x16x32_bf16 v[8:11], v[140:143], v[216:219], v[8:11]
	v_mfma_f32_16x16x32_bf16 v[52:55], v[162:165], v[178:181], v[52:55]
	v_mfma_f32_16x16x32_bf16 v[48:51], v[170:173], v[178:181], v[48:51]
	v_mfma_f32_16x16x32_bf16 v[36:39], v[162:165], v[196:199], v[36:39]
	v_mfma_f32_16x16x32_bf16 v[32:35], v[170:173], v[196:199], v[32:35]
	v_mfma_f32_16x16x32_bf16 v[20:23], v[162:165], v[204:207], v[20:23]
	v_mfma_f32_16x16x32_bf16 v[16:19], v[170:173], v[204:207], v[16:19]
	v_mfma_f32_16x16x32_bf16 v[4:7], v[162:165], v[212:215], v[4:7]
	v_mfma_f32_16x16x32_bf16 v[0:3], v[170:173], v[212:215], v[0:3]
	v_mfma_f32_16x16x32_bf16 v[52:55], v[166:169], v[192:195], v[52:55]
	v_mfma_f32_16x16x32_bf16 v[48:51], v[174:177], v[192:195], v[48:51]
	v_mfma_f32_16x16x32_bf16 v[36:39], v[166:169], v[200:203], v[36:39]
	v_mfma_f32_16x16x32_bf16 v[32:35], v[174:177], v[200:203], v[32:35]
	v_mfma_f32_16x16x32_bf16 v[20:23], v[166:169], v[208:211], v[20:23]
	v_mfma_f32_16x16x32_bf16 v[16:19], v[174:177], v[208:211], v[16:19]
	v_mfma_f32_16x16x32_bf16 v[4:7], v[166:169], v[216:219], v[4:7]
	v_mfma_f32_16x16x32_bf16 v[0:3], v[174:177], v[216:219], v[0:3]
	s_setprio 0
	s_barrier
	s_add_i32 s57, 0, 0x18000
	s_add_i32 s58, 0, 0x1c000
	v_add_u32_e32 v140, s57, v184
	v_add_u32_e32 v174, s58, v184
	ds_read_b128 v[128:131], v140
	ds_read_b128 v[132:135], v140 offset:1024
	ds_read_b128 v[136:139], v140 offset:2048
	ds_read_b128 v[140:143], v140 offset:3072
	ds_read_b128 v[162:165], v174
	ds_read_b128 v[166:169], v174 offset:1024
	ds_read_b128 v[170:173], v174 offset:2048
	ds_read_b128 v[174:177], v174 offset:3072
	s_add_u32 s40, s40, 0x80000
	s_addc_u32 s41, s41, 0
	s_mov_b32 m0, s44
	v_lshl_add_u64 v[226:227], s[40:41], 0, v[150:151]
	ds_read_b128 v[178:181], v188 offset:32768
	ds_read_b128 v[192:195], v188 offset:33792
	ds_read_b128 v[196:199], v188 offset:34816
	ds_read_b128 v[200:203], v188 offset:35840
	ds_read_b128 v[204:207], v188 offset:36864
	ds_read_b128 v[208:211], v188 offset:37888
	ds_read_b128 v[212:215], v188 offset:38912
	ds_read_b128 v[216:219], v188 offset:39936
	global_load_lds_dwordx4 v[226:227], off
	v_lshl_add_u64 v[226:227], s[40:41], 0, v[146:147]
	s_mov_b32 m0, s45
	s_nop 0
	global_load_lds_dwordx4 v[226:227], off
	s_waitcnt vmcnt(8)
	s_waitcnt lgkmcnt(0)
	s_barrier
	s_setprio 1
	s_waitcnt lgkmcnt(0)
	v_mfma_f32_16x16x32_bf16 v[124:127], v[128:131], v[178:181], v[124:127]
	v_mfma_f32_16x16x32_bf16 v[120:123], v[136:139], v[178:181], v[120:123]
	v_mfma_f32_16x16x32_bf16 v[108:111], v[128:131], v[196:199], v[108:111]
	v_mfma_f32_16x16x32_bf16 v[104:107], v[136:139], v[196:199], v[104:107]
	v_mfma_f32_16x16x32_bf16 v[92:95], v[128:131], v[204:207], v[92:95]
	v_mfma_f32_16x16x32_bf16 v[88:91], v[136:139], v[204:207], v[88:91]
	v_mfma_f32_16x16x32_bf16 v[76:79], v[128:131], v[212:215], v[76:79]
	v_mfma_f32_16x16x32_bf16 v[72:75], v[136:139], v[212:215], v[72:75]
	v_mfma_f32_16x16x32_bf16 v[124:127], v[132:135], v[192:195], v[124:127]
	v_mfma_f32_16x16x32_bf16 v[120:123], v[140:143], v[192:195], v[120:123]
	v_mfma_f32_16x16x32_bf16 v[108:111], v[132:135], v[200:203], v[108:111]
	v_mfma_f32_16x16x32_bf16 v[104:107], v[140:143], v[200:203], v[104:107]
	v_mfma_f32_16x16x32_bf16 v[92:95], v[132:135], v[208:211], v[92:95]
	v_mfma_f32_16x16x32_bf16 v[88:91], v[140:143], v[208:211], v[88:91]
	v_mfma_f32_16x16x32_bf16 v[76:79], v[132:135], v[216:219], v[76:79]
	v_mfma_f32_16x16x32_bf16 v[72:75], v[140:143], v[216:219], v[72:75]
	v_mfma_f32_16x16x32_bf16 v[116:119], v[162:165], v[178:181], v[116:119]
	v_mfma_f32_16x16x32_bf16 v[112:115], v[170:173], v[178:181], v[112:115]
	v_mfma_f32_16x16x32_bf16 v[100:103], v[162:165], v[196:199], v[100:103]
	v_mfma_f32_16x16x32_bf16 v[96:99], v[170:173], v[196:199], v[96:99]
	v_mfma_f32_16x16x32_bf16 v[84:87], v[162:165], v[204:207], v[84:87]
	v_mfma_f32_16x16x32_bf16 v[80:83], v[170:173], v[204:207], v[80:83]
	v_mfma_f32_16x16x32_bf16 v[68:71], v[162:165], v[212:215], v[68:71]
	v_mfma_f32_16x16x32_bf16 v[64:67], v[170:173], v[212:215], v[64:67]
	v_mfma_f32_16x16x32_bf16 v[116:119], v[166:169], v[192:195], v[116:119]
	v_mfma_f32_16x16x32_bf16 v[112:115], v[174:177], v[192:195], v[112:115]
	v_mfma_f32_16x16x32_bf16 v[100:103], v[166:169], v[200:203], v[100:103]
	v_mfma_f32_16x16x32_bf16 v[96:99], v[174:177], v[200:203], v[96:99]
	v_mfma_f32_16x16x32_bf16 v[84:87], v[166:169], v[208:211], v[84:87]
	v_mfma_f32_16x16x32_bf16 v[80:83], v[174:177], v[208:211], v[80:83]
	v_mfma_f32_16x16x32_bf16 v[68:71], v[166:169], v[216:219], v[68:71]
	v_mfma_f32_16x16x32_bf16 v[64:67], v[174:177], v[216:219], v[64:67]
	s_setprio 0
	s_barrier
	s_add_i32 s40, s57, s35
	v_lshl_add_u64 v[182:183], v[182:183], 0, s[14:15]
	s_mov_b32 m0, s40
	ds_read_b128 v[178:181], v188 offset:49152
	ds_read_b128 v[192:195], v188 offset:50176
	ds_read_b128 v[196:199], v188 offset:51200
	ds_read_b128 v[200:203], v188 offset:52224
	ds_read_b128 v[204:207], v188 offset:53248
	ds_read_b128 v[208:211], v188 offset:54272
	ds_read_b128 v[212:215], v188 offset:55296
	ds_read_b128 v[216:219], v188 offset:56320
	global_load_lds_dwordx4 v[182:183], off
	s_add_i32 m0, s40, 0x2000
	s_add_u32 s38, s38, 0x80080
	v_lshl_add_u64 v[182:183], v[220:221], 0, s[14:15]
	s_addc_u32 s39, s39, 0
	s_add_i32 s40, s58, s35
	global_load_lds_dwordx4 v[182:183], off
	v_lshl_add_u64 v[182:183], s[38:39], 0, v[148:149]
	s_mov_b32 m0, s40
	s_nop 0
	global_load_lds_dwordx4 v[182:183], off
	v_lshl_add_u64 v[182:183], s[38:39], 0, v[144:145]
	s_add_i32 m0, s40, 0x2000
	s_nop 0
	global_load_lds_dwordx4 v[182:183], off
	v_lshl_add_u64 v[182:183], v[222:223], 0, s[14:15]
	s_mov_b32 m0, s49
	s_nop 0
	global_load_lds_dwordx4 v[182:183], off
	v_lshl_add_u64 v[182:183], v[224:225], 0, s[14:15]
	s_mov_b32 m0, s50
	s_nop 0
	global_load_lds_dwordx4 v[182:183], off
	s_waitcnt vmcnt(8)
	s_waitcnt lgkmcnt(0)
	s_barrier
	s_setprio 1
	s_waitcnt lgkmcnt(0)
	v_mfma_f32_16x16x32_bf16 v[60:63], v[128:131], v[178:181], v[60:63]
	v_mfma_f32_16x16x32_bf16 v[56:59], v[136:139], v[178:181], v[56:59]
	v_mfma_f32_16x16x32_bf16 v[44:47], v[128:131], v[196:199], v[44:47]
	v_mfma_f32_16x16x32_bf16 v[40:43], v[136:139], v[196:199], v[40:43]
	v_mfma_f32_16x16x32_bf16 v[28:31], v[128:131], v[204:207], v[28:31]
	v_mfma_f32_16x16x32_bf16 v[24:27], v[136:139], v[204:207], v[24:27]
	v_mfma_f32_16x16x32_bf16 v[12:15], v[128:131], v[212:215], v[12:15]
	v_mfma_f32_16x16x32_bf16 v[8:11], v[136:139], v[212:215], v[8:11]
	v_mfma_f32_16x16x32_bf16 v[60:63], v[132:135], v[192:195], v[60:63]
	v_mfma_f32_16x16x32_bf16 v[56:59], v[140:143], v[192:195], v[56:59]
	v_mfma_f32_16x16x32_bf16 v[44:47], v[132:135], v[200:203], v[44:47]
	v_mfma_f32_16x16x32_bf16 v[40:43], v[140:143], v[200:203], v[40:43]
	v_mfma_f32_16x16x32_bf16 v[28:31], v[132:135], v[208:211], v[28:31]
	v_mfma_f32_16x16x32_bf16 v[24:27], v[140:143], v[208:211], v[24:27]
	v_mfma_f32_16x16x32_bf16 v[12:15], v[132:135], v[216:219], v[12:15]
	v_mfma_f32_16x16x32_bf16 v[8:11], v[140:143], v[216:219], v[8:11]
	v_mfma_f32_16x16x32_bf16 v[52:55], v[162:165], v[178:181], v[52:55]
	v_mfma_f32_16x16x32_bf16 v[48:51], v[170:173], v[178:181], v[48:51]
	v_mfma_f32_16x16x32_bf16 v[36:39], v[162:165], v[196:199], v[36:39]
	v_mfma_f32_16x16x32_bf16 v[32:35], v[170:173], v[196:199], v[32:35]
	v_mfma_f32_16x16x32_bf16 v[20:23], v[162:165], v[204:207], v[20:23]
	v_mfma_f32_16x16x32_bf16 v[16:19], v[170:173], v[204:207], v[16:19]
	v_mfma_f32_16x16x32_bf16 v[4:7], v[162:165], v[212:215], v[4:7]
	v_mfma_f32_16x16x32_bf16 v[0:3], v[170:173], v[212:215], v[0:3]
	v_mfma_f32_16x16x32_bf16 v[52:55], v[166:169], v[192:195], v[52:55]
	v_mfma_f32_16x16x32_bf16 v[48:51], v[174:177], v[192:195], v[48:51]
	v_mfma_f32_16x16x32_bf16 v[36:39], v[166:169], v[200:203], v[36:39]
	v_mfma_f32_16x16x32_bf16 v[32:35], v[174:177], v[200:203], v[32:35]
	v_mfma_f32_16x16x32_bf16 v[20:23], v[166:169], v[208:211], v[20:23]
	v_mfma_f32_16x16x32_bf16 v[16:19], v[174:177], v[208:211], v[16:19]
	v_mfma_f32_16x16x32_bf16 v[4:7], v[166:169], v[216:219], v[4:7]
	v_mfma_f32_16x16x32_bf16 v[0:3], v[174:177], v[216:219], v[0:3]
	s_setprio 0
	s_barrier
	s_add_i32 s56, s56, 2
	s_add_u32 s6, s6, 0x100
	s_addc_u32 s7, s7, 0
	s_add_u32 s5, s5, 0x100
	s_addc_u32 s25, s25, 0
	s_cmp_gt_u32 s56, 29
	s_cbranch_scc0 .LBB0_672
	s_and_b64 vcc, exec, s[18:19]
	s_cbranch_vccz .LBB0_675
	s_barrier
